# attention queue order: chunk-band blk1 group (8 tile steps) moved from position 6 to position 11 of each per-XCD queue (after stick-breaking blk 7..3)
# speedup vs baseline: 1.0048x; 1.0048x over previous
.LBB0_261:
	s_lshl_b32 s0, s52, 3
	s_add_i32 s0, s0, 0
	s_add_i32 s0, s0, 0x19440
	v_mov_b32_e32 v0, s0
	s_waitcnt lgkmcnt(0)
	s_barrier
	ds_read_b64 v[2:3], v0
	s_waitcnt lgkmcnt(0)
	v_readfirstlane_b32 s8, v2
	s_cmp_lt_i32 s8, 0
	v_readfirstlane_b32 s20, v3
	s_cbranch_scc1 .LBB0_309
	s_lshr_b32 s12, s8, 2
	s_lshl_b32 s12, s12, 2
	s_mov_b32 s14, 0x87543210
	s_mov_b32 s15, 0xfedc6ba9
	s_lshr_b64 s[14:15], s[14:15], s12
	s_and_b32 s14, s14, 15
	s_and_b32 s13, s8, 3
	s_lshl_b32 s14, s14, 2
	s_or_b32 s8, s14, s13
	s_lshr_b32 s9, s8, 2
	s_cmp_gt_u32 s8, 23
	s_mov_b64 s[2:3], -1
	s_cbranch_scc0 .LBB0_268
	s_mov_b64 s[2:3], 0
	s_mov_b32 s98, 1
	s_cmp_eq_u32 s9, 6
	s_mov_b64 s[0:1], 0
	s_cbranch_scc1 .LBB0_268
	s_cmp_gt_u32 s8, 55
	s_mov_b64 s[6:7], -1
	s_cbranch_scc0 .LBB0_266
	s_cmp_lg_u32 s9, 14
	s_mov_b64 s[6:7], 0
	s_cselect_b64 s[0:1], -1, 0
